# LDS-DMA K-loop rolled out to gemm1, ffn-in, out-proj and ffn-out GEMM sites (branch GEMM unchanged)
# speedup vs baseline: 1.0873x; 1.0377x over previous
.LBB0_157:
	s_andn2_b64 vcc, exec, s[20:21]
	s_cbranch_vccnz .LBB0_154
	s_lshl_b32 s21, s46, 7
	v_lshlrev_b32_e32 v0, 3, v108
	s_and_b32 s49, s21, 0x380
	v_ashrrev_i32_e32 v36, 3, v108
	v_and_b32_e32 v37, 56, v0
	v_add_u32_e32 v0, s49, v36
	s_movk_i32 s24, 0xb00
	s_lshl_b32 s20, s46, 4
	v_mul_lo_u32 v0, v0, s24
	s_and_b32 s47, s20, 0xffffff80
	v_or_b32_e32 v0, v0, v37
	s_waitcnt lgkmcnt(0)
	v_lshl_add_u64 v[2:3], v[0:1], 1, s[26:27]
	v_add_u32_e32 v0, s47, v36
	v_mul_lo_u32 v0, v0, s24
	v_or_b32_e32 v0, v0, v37
	v_lshl_add_u64 v[12:13], v[0:1], 1, s[90:91]
	v_mov_b32_e32 v74, v12
	v_mov_b32_e32 v75, v13
	v_mov_b32_e32 v72, v2
	v_mov_b32_e32 v73, v3
	v_mov_b32_e32 v104, 0x2c000
	v_mov_b32_e32 v105, 0
	v_lshl_add_u64 v[76:77], v[74:75], 0, v[104:105]
	v_lshl_add_u64 v[78:79], v[76:77], 0, v[104:105]
	v_lshl_add_u64 v[80:81], v[78:79], 0, v[104:105]
	v_lshl_add_u64 v[82:83], v[72:73], 0, v[104:105]
	v_lshl_add_u64 v[84:85], v[82:83], 0, v[104:105]
	v_lshl_add_u64 v[86:87], v[84:85], 0, v[104:105]
	v_and_b32_e32 v110, 31, v108
	v_ashrrev_i32_e32 v0, 1, v108
	v_and_b32_e32 v111, 0xffffffc0, v0
	v_readlane_b32 s52, v252, 4
	v_readlane_b32 s66, v252, 18
	v_readlane_b32 s67, v252, 19
	v_readlane_b32 s53, v252, 5
	v_readlane_b32 s54, v252, 6
	v_readlane_b32 s55, v252, 7
	v_readlane_b32 s56, v252, 8
	v_readlane_b32 s57, v252, 9
	v_readlane_b32 s58, v252, 10
	v_readlane_b32 s59, v252, 11
	v_readlane_b32 s60, v252, 12
	v_readlane_b32 s61, v252, 13
	v_readlane_b32 s62, v252, 14
	v_readlane_b32 s63, v252, 15
	v_readlane_b32 s64, v252, 16
	v_readlane_b32 s65, v252, 17
	s_barrier
	v_bfe_u32 v102, v108, 4, 3
	v_lshlrev_b32_e32 v102, 4, v102
	v_xor_b32_e32 v74, v102, v74
	v_xor_b32_e32 v76, v102, v76
	v_xor_b32_e32 v78, v102, v78
	v_xor_b32_e32 v80, v102, v80
	v_xor_b32_e32 v72, v102, v72
	v_xor_b32_e32 v82, v102, v82
	v_xor_b32_e32 v84, v102, v84
	v_xor_b32_e32 v86, v102, v86
	v_bfe_u32 v102, v108, 5, 1
	v_bfe_u32 v103, v108, 1, 3
	v_xor_b32_e32 v102, v102, v103
	v_lshlrev_b32_e32 v102, 4, v102
	v_lshrrev_b32_e32 v103, 1, v108
	v_and_b32_e32 v103, 64, v103
	v_and_b32_e32 v104, 31, v108
	v_or_b32_e32 v103, v103, v104
	v_lshl_or_b32 v94, v103, 7, v102
	v_and_b32_e32 v103, 0x5f, v108
	v_lshl_or_b32 v98, v103, 7, v102
	v_add_u32_e32 v98, 0x4000, v98
	v_xor_b32_e32 v95, 0x20, v94
	v_xor_b32_e32 v99, 0x20, v98
	v_xor_b32_e32 v96, 0x40, v94
	v_xor_b32_e32 v100, 0x40, v98
	v_xor_b32_e32 v97, 0x60, v94
	v_xor_b32_e32 v101, 0x60, v98
	v_mov_b32_e32 v214, 0x80
	v_mov_b32_e32 v215, 0
	s_lshl_b32 vcc_lo, s80, 4
	v_mov_b32_e32 v2, 0
	v_mov_b32_e32 v3, 0
	v_mov_b32_e32 v4, 0
	v_mov_b32_e32 v5, 0
	v_mov_b32_e32 v6, 0
	v_mov_b32_e32 v7, 0
	v_mov_b32_e32 v8, 0
	v_mov_b32_e32 v9, 0
	v_mov_b32_e32 v10, 0
	v_mov_b32_e32 v11, 0
	v_mov_b32_e32 v12, 0
	v_mov_b32_e32 v13, 0
	v_mov_b32_e32 v14, 0
	v_mov_b32_e32 v15, 0
	v_mov_b32_e32 v16, 0
	v_mov_b32_e32 v17, 0
	v_mov_b32_e32 v18, 0
	v_mov_b32_e32 v19, 0
	v_mov_b32_e32 v20, 0
	v_mov_b32_e32 v21, 0
	v_mov_b32_e32 v22, 0
	v_mov_b32_e32 v23, 0
	v_mov_b32_e32 v24, 0
	v_mov_b32_e32 v25, 0
	v_mov_b32_e32 v26, 0
	v_mov_b32_e32 v27, 0
	v_mov_b32_e32 v28, 0
	v_mov_b32_e32 v29, 0
	v_mov_b32_e32 v30, 0
	v_mov_b32_e32 v31, 0
	v_mov_b32_e32 v32, 0
	v_mov_b32_e32 v33, 0
	v_mov_b32_e32 v34, 0
	v_mov_b32_e32 v35, 0
	v_mov_b32_e32 v36, 0
	v_mov_b32_e32 v37, 0
	v_mov_b32_e32 v38, 0
	v_mov_b32_e32 v39, 0
	v_mov_b32_e32 v40, 0
	v_mov_b32_e32 v41, 0
	v_mov_b32_e32 v42, 0
	v_mov_b32_e32 v43, 0
	v_mov_b32_e32 v44, 0
	v_mov_b32_e32 v45, 0
	v_mov_b32_e32 v46, 0
	v_mov_b32_e32 v47, 0
	v_mov_b32_e32 v48, 0
	v_mov_b32_e32 v49, 0
	v_mov_b32_e32 v50, 0
	v_mov_b32_e32 v51, 0
	v_mov_b32_e32 v52, 0
	v_mov_b32_e32 v53, 0
	v_mov_b32_e32 v54, 0
	v_mov_b32_e32 v55, 0
	v_mov_b32_e32 v56, 0
	v_mov_b32_e32 v57, 0
	v_mov_b32_e32 v58, 0
	v_mov_b32_e32 v59, 0
	v_mov_b32_e32 v60, 0
	v_mov_b32_e32 v61, 0
	v_mov_b32_e32 v62, 0
	v_mov_b32_e32 v63, 0
	v_mov_b32_e32 v64, 0
	v_mov_b32_e32 v65, 0
	s_mov_b32 m0, vcc_lo
	s_nop 0
	global_load_lds_dwordx4 v[74:75], off
	s_add_u32 m0, vcc_lo, 0x1000
	s_nop 0
	global_load_lds_dwordx4 v[76:77], off
	s_add_u32 m0, vcc_lo, 0x2000
	s_nop 0
	global_load_lds_dwordx4 v[78:79], off
	s_add_u32 m0, vcc_lo, 0x3000
	s_nop 0
	global_load_lds_dwordx4 v[80:81], off
	s_add_u32 m0, vcc_lo, 0x4000
	s_nop 0
	global_load_lds_dwordx4 v[72:73], off
	s_add_u32 m0, vcc_lo, 0x5000
	s_nop 0
	global_load_lds_dwordx4 v[82:83], off
	s_add_u32 m0, vcc_lo, 0x6000
	s_nop 0
	global_load_lds_dwordx4 v[84:85], off
	s_add_u32 m0, vcc_lo, 0x7000
	s_nop 0
	global_load_lds_dwordx4 v[86:87], off
	v_lshl_add_u64 v[74:75], v[74:75], 0, v[214:215]
	v_lshl_add_u64 v[76:77], v[76:77], 0, v[214:215]
	v_lshl_add_u64 v[78:79], v[78:79], 0, v[214:215]
	v_lshl_add_u64 v[80:81], v[80:81], 0, v[214:215]
	v_lshl_add_u64 v[72:73], v[72:73], 0, v[214:215]
	v_lshl_add_u64 v[82:83], v[82:83], 0, v[214:215]
	v_lshl_add_u64 v[84:85], v[84:85], 0, v[214:215]
	v_lshl_add_u64 v[86:87], v[86:87], 0, v[214:215]
	s_add_u32 m0, vcc_lo, 0x8000
	s_nop 0
	global_load_lds_dwordx4 v[74:75], off
	s_add_u32 m0, vcc_lo, 0x9000
	s_nop 0
	global_load_lds_dwordx4 v[76:77], off
	s_add_u32 m0, vcc_lo, 0xa000
	s_nop 0
	global_load_lds_dwordx4 v[78:79], off
	s_add_u32 m0, vcc_lo, 0xb000
	s_nop 0
	global_load_lds_dwordx4 v[80:81], off
	s_add_u32 m0, vcc_lo, 0xc000
	s_nop 0
	global_load_lds_dwordx4 v[72:73], off
	s_add_u32 m0, vcc_lo, 0xd000
	s_nop 0
	global_load_lds_dwordx4 v[82:83], off
	s_add_u32 m0, vcc_lo, 0xe000
	s_nop 0
	global_load_lds_dwordx4 v[84:85], off
	s_add_u32 m0, vcc_lo, 0xf000
	s_nop 0
	global_load_lds_dwordx4 v[86:87], off
	v_lshl_add_u64 v[74:75], v[74:75], 0, v[214:215]
	v_lshl_add_u64 v[76:77], v[76:77], 0, v[214:215]
	v_lshl_add_u64 v[78:79], v[78:79], 0, v[214:215]
	v_lshl_add_u64 v[80:81], v[80:81], 0, v[214:215]
	v_lshl_add_u64 v[72:73], v[72:73], 0, v[214:215]
	v_lshl_add_u64 v[82:83], v[82:83], 0, v[214:215]
	v_lshl_add_u64 v[84:85], v[84:85], 0, v[214:215]
	v_lshl_add_u64 v[86:87], v[86:87], 0, v[214:215]
	s_mov_b32 vcc_hi, 21
	s_waitcnt vmcnt(8)
	s_barrier
	ds_read_b128 v[166:169], v94
	ds_read_b128 v[170:173], v98
	ds_read_b128 v[174:177], v98 offset:4096
	ds_read_b128 v[178:181], v94 offset:4096
	ds_read_b128 v[182:185], v95
	ds_read_b128 v[188:191], v99
	ds_read_b128 v[192:195], v99 offset:4096
	ds_read_b128 v[206:209], v95 offset:4096
	s_waitcnt lgkmcnt(6)
	v_mfma_f32_32x32x16_bf16 v[50:65], v[166:169], v[170:173], v[50:65]
	ds_read_b128 v[236:239], v96
	s_waitcnt lgkmcnt(6)
	v_mfma_f32_32x32x16_bf16 v[34:49], v[166:169], v[174:177], v[34:49]
	ds_read_b128 v[240:243], v100
	s_waitcnt lgkmcnt(6)
	v_mfma_f32_32x32x16_bf16 v[18:33], v[178:181], v[170:173], v[18:33]
	ds_read_b128 v[244:247], v100 offset:4096
	v_mfma_f32_32x32x16_bf16 v[2:17], v[178:181], v[174:177], v[2:17]
	ds_read_b128 v[248:251], v96 offset:4096
	s_waitcnt lgkmcnt(6)
	v_mfma_f32_32x32x16_bf16 v[50:65], v[182:185], v[188:191], v[50:65]
	ds_read_b128 v[126:129], v97
	s_waitcnt lgkmcnt(6)
	v_mfma_f32_32x32x16_bf16 v[34:49], v[182:185], v[192:195], v[34:49]
	ds_read_b128 v[130:133], v101
	s_waitcnt lgkmcnt(6)
	v_mfma_f32_32x32x16_bf16 v[18:33], v[206:209], v[188:191], v[18:33]
	ds_read_b128 v[210:213], v101 offset:4096
	v_mfma_f32_32x32x16_bf16 v[2:17], v[206:209], v[192:195], v[2:17]
	ds_read_b128 v[222:225], v97 offset:4096
	s_waitcnt vmcnt(0) lgkmcnt(0)
	s_barrier
.Lg_resid1_loop:
	v_mfma_f32_32x32x16_bf16 v[50:65], v[236:239], v[240:243], v[50:65]
	s_mov_b32 m0, vcc_lo
	ds_read_b128 v[166:169], v94 offset:32768
	global_load_lds_dwordx4 v[74:75], off
	v_mfma_f32_32x32x16_bf16 v[34:49], v[236:239], v[244:247], v[34:49]
	s_add_u32 m0, vcc_lo, 0x1000
	ds_read_b128 v[170:173], v98 offset:32768
	global_load_lds_dwordx4 v[76:77], off
	v_mfma_f32_32x32x16_bf16 v[18:33], v[248:251], v[240:243], v[18:33]
	s_add_u32 m0, vcc_lo, 0x2000
	ds_read_b128 v[174:177], v98 offset:36864
	global_load_lds_dwordx4 v[78:79], off
	v_mfma_f32_32x32x16_bf16 v[2:17], v[248:251], v[244:247], v[2:17]
	s_add_u32 m0, vcc_lo, 0x3000
	ds_read_b128 v[178:181], v94 offset:36864
	global_load_lds_dwordx4 v[80:81], off
	v_mfma_f32_32x32x16_bf16 v[50:65], v[126:129], v[130:133], v[50:65]
	s_add_u32 m0, vcc_lo, 0x4000
	ds_read_b128 v[182:185], v95 offset:32768
	global_load_lds_dwordx4 v[72:73], off
	v_mfma_f32_32x32x16_bf16 v[34:49], v[126:129], v[210:213], v[34:49]
	s_add_u32 m0, vcc_lo, 0x5000
	ds_read_b128 v[188:191], v99 offset:32768
	global_load_lds_dwordx4 v[82:83], off
	v_mfma_f32_32x32x16_bf16 v[18:33], v[222:225], v[130:133], v[18:33]
	s_add_u32 m0, vcc_lo, 0x6000
	ds_read_b128 v[192:195], v99 offset:36864
	global_load_lds_dwordx4 v[84:85], off
	v_mfma_f32_32x32x16_bf16 v[2:17], v[222:225], v[210:213], v[2:17]
	s_add_u32 m0, vcc_lo, 0x7000
	ds_read_b128 v[206:209], v95 offset:36864
	global_load_lds_dwordx4 v[86:87], off
	s_waitcnt lgkmcnt(6)
	v_mfma_f32_32x32x16_bf16 v[50:65], v[166:169], v[170:173], v[50:65]
	ds_read_b128 v[236:239], v96 offset:32768
	v_lshl_add_u64 v[74:75], v[74:75], 0, v[214:215]
	v_lshl_add_u64 v[76:77], v[76:77], 0, v[214:215]
	v_lshl_add_u64 v[78:79], v[78:79], 0, v[214:215]
	v_lshl_add_u64 v[80:81], v[80:81], 0, v[214:215]
	v_lshl_add_u64 v[72:73], v[72:73], 0, v[214:215]
	v_lshl_add_u64 v[82:83], v[82:83], 0, v[214:215]
	v_lshl_add_u64 v[84:85], v[84:85], 0, v[214:215]
	v_lshl_add_u64 v[86:87], v[86:87], 0, v[214:215]
	s_waitcnt lgkmcnt(6)
	v_mfma_f32_32x32x16_bf16 v[34:49], v[166:169], v[174:177], v[34:49]
	ds_read_b128 v[240:243], v100 offset:32768
	s_waitcnt lgkmcnt(6)
	v_mfma_f32_32x32x16_bf16 v[18:33], v[178:181], v[170:173], v[18:33]
	ds_read_b128 v[244:247], v100 offset:36864
	v_mfma_f32_32x32x16_bf16 v[2:17], v[178:181], v[174:177], v[2:17]
	ds_read_b128 v[248:251], v96 offset:36864
	s_waitcnt lgkmcnt(6)
	v_mfma_f32_32x32x16_bf16 v[50:65], v[182:185], v[188:191], v[50:65]
	ds_read_b128 v[126:129], v97 offset:32768
	s_waitcnt lgkmcnt(6)
	v_mfma_f32_32x32x16_bf16 v[34:49], v[182:185], v[192:195], v[34:49]
	ds_read_b128 v[130:133], v101 offset:32768
	s_waitcnt lgkmcnt(6)
	v_mfma_f32_32x32x16_bf16 v[18:33], v[206:209], v[188:191], v[18:33]
	ds_read_b128 v[210:213], v101 offset:36864
	v_mfma_f32_32x32x16_bf16 v[2:17], v[206:209], v[192:195], v[2:17]
	ds_read_b128 v[222:225], v97 offset:36864
	s_waitcnt vmcnt(0) lgkmcnt(0)
	s_barrier
	v_mfma_f32_32x32x16_bf16 v[50:65], v[236:239], v[240:243], v[50:65]
	s_add_u32 m0, vcc_lo, 0x8000
	ds_read_b128 v[166:169], v94
	global_load_lds_dwordx4 v[74:75], off
	v_mfma_f32_32x32x16_bf16 v[34:49], v[236:239], v[244:247], v[34:49]
	s_add_u32 m0, vcc_lo, 0x9000
	ds_read_b128 v[170:173], v98
	global_load_lds_dwordx4 v[76:77], off
	v_mfma_f32_32x32x16_bf16 v[18:33], v[248:251], v[240:243], v[18:33]
	s_add_u32 m0, vcc_lo, 0xa000
	ds_read_b128 v[174:177], v98 offset:4096
	global_load_lds_dwordx4 v[78:79], off
	v_mfma_f32_32x32x16_bf16 v[2:17], v[248:251], v[244:247], v[2:17]
	s_add_u32 m0, vcc_lo, 0xb000
	ds_read_b128 v[178:181], v94 offset:4096
	global_load_lds_dwordx4 v[80:81], off
	v_mfma_f32_32x32x16_bf16 v[50:65], v[126:129], v[130:133], v[50:65]
	s_add_u32 m0, vcc_lo, 0xc000
	ds_read_b128 v[182:185], v95
	global_load_lds_dwordx4 v[72:73], off
	v_mfma_f32_32x32x16_bf16 v[34:49], v[126:129], v[210:213], v[34:49]
	s_add_u32 m0, vcc_lo, 0xd000
	ds_read_b128 v[188:191], v99
	global_load_lds_dwordx4 v[82:83], off
	v_mfma_f32_32x32x16_bf16 v[18:33], v[222:225], v[130:133], v[18:33]
	s_add_u32 m0, vcc_lo, 0xe000
	ds_read_b128 v[192:195], v99 offset:4096
	global_load_lds_dwordx4 v[84:85], off
	v_mfma_f32_32x32x16_bf16 v[2:17], v[222:225], v[210:213], v[2:17]
	s_add_u32 m0, vcc_lo, 0xf000
	ds_read_b128 v[206:209], v95 offset:4096
	global_load_lds_dwordx4 v[86:87], off
	s_waitcnt lgkmcnt(6)
	v_mfma_f32_32x32x16_bf16 v[50:65], v[166:169], v[170:173], v[50:65]
	ds_read_b128 v[236:239], v96
	v_lshl_add_u64 v[74:75], v[74:75], 0, v[214:215]
	v_lshl_add_u64 v[76:77], v[76:77], 0, v[214:215]
	v_lshl_add_u64 v[78:79], v[78:79], 0, v[214:215]
	v_lshl_add_u64 v[80:81], v[80:81], 0, v[214:215]
	v_lshl_add_u64 v[72:73], v[72:73], 0, v[214:215]
	v_lshl_add_u64 v[82:83], v[82:83], 0, v[214:215]
	v_lshl_add_u64 v[84:85], v[84:85], 0, v[214:215]
	v_lshl_add_u64 v[86:87], v[86:87], 0, v[214:215]
	s_waitcnt lgkmcnt(6)
	v_mfma_f32_32x32x16_bf16 v[34:49], v[166:169], v[174:177], v[34:49]
	ds_read_b128 v[240:243], v100
	s_waitcnt lgkmcnt(6)
	v_mfma_f32_32x32x16_bf16 v[18:33], v[178:181], v[170:173], v[18:33]
	ds_read_b128 v[244:247], v100 offset:4096
	v_mfma_f32_32x32x16_bf16 v[2:17], v[178:181], v[174:177], v[2:17]
	ds_read_b128 v[248:251], v96 offset:4096
	s_waitcnt lgkmcnt(6)
	v_mfma_f32_32x32x16_bf16 v[50:65], v[182:185], v[188:191], v[50:65]
	ds_read_b128 v[126:129], v97
	s_waitcnt lgkmcnt(6)
	v_mfma_f32_32x32x16_bf16 v[34:49], v[182:185], v[192:195], v[34:49]
	ds_read_b128 v[130:133], v101
	s_waitcnt lgkmcnt(6)
	v_mfma_f32_32x32x16_bf16 v[18:33], v[206:209], v[188:191], v[18:33]
	ds_read_b128 v[210:213], v101 offset:4096
	v_mfma_f32_32x32x16_bf16 v[2:17], v[206:209], v[192:195], v[2:17]
	ds_read_b128 v[222:225], v97 offset:4096
	s_waitcnt vmcnt(0) lgkmcnt(0)
	s_barrier
	s_sub_u32 vcc_hi, vcc_hi, 1
	s_cmp_lg_u32 vcc_hi, 0
	s_cbranch_scc1 .Lg_resid1_loop
	v_mfma_f32_32x32x16_bf16 v[50:65], v[236:239], v[240:243], v[50:65]
	ds_read_b128 v[166:169], v94 offset:32768
	v_mfma_f32_32x32x16_bf16 v[34:49], v[236:239], v[244:247], v[34:49]
	ds_read_b128 v[170:173], v98 offset:32768
	v_mfma_f32_32x32x16_bf16 v[18:33], v[248:251], v[240:243], v[18:33]
	ds_read_b128 v[174:177], v98 offset:36864
	v_mfma_f32_32x32x16_bf16 v[2:17], v[248:251], v[244:247], v[2:17]
	ds_read_b128 v[178:181], v94 offset:36864
	v_mfma_f32_32x32x16_bf16 v[50:65], v[126:129], v[130:133], v[50:65]
	ds_read_b128 v[182:185], v95 offset:32768
	v_mfma_f32_32x32x16_bf16 v[34:49], v[126:129], v[210:213], v[34:49]
	ds_read_b128 v[188:191], v99 offset:32768
	v_mfma_f32_32x32x16_bf16 v[18:33], v[222:225], v[130:133], v[18:33]
	ds_read_b128 v[192:195], v99 offset:36864
	v_mfma_f32_32x32x16_bf16 v[2:17], v[222:225], v[210:213], v[2:17]
	ds_read_b128 v[206:209], v95 offset:36864
	s_waitcnt lgkmcnt(6)
	v_mfma_f32_32x32x16_bf16 v[50:65], v[166:169], v[170:173], v[50:65]
	ds_read_b128 v[236:239], v96 offset:32768
	s_waitcnt lgkmcnt(6)
	v_mfma_f32_32x32x16_bf16 v[34:49], v[166:169], v[174:177], v[34:49]
	ds_read_b128 v[240:243], v100 offset:32768
	s_waitcnt lgkmcnt(6)
	v_mfma_f32_32x32x16_bf16 v[18:33], v[178:181], v[170:173], v[18:33]
	ds_read_b128 v[244:247], v100 offset:36864
	v_mfma_f32_32x32x16_bf16 v[2:17], v[178:181], v[174:177], v[2:17]
	ds_read_b128 v[248:251], v96 offset:36864
	s_waitcnt lgkmcnt(6)
	v_mfma_f32_32x32x16_bf16 v[50:65], v[182:185], v[188:191], v[50:65]
	ds_read_b128 v[126:129], v97 offset:32768
	s_waitcnt lgkmcnt(6)
	v_mfma_f32_32x32x16_bf16 v[34:49], v[182:185], v[192:195], v[34:49]
	ds_read_b128 v[130:133], v101 offset:32768
	s_waitcnt lgkmcnt(6)
	v_mfma_f32_32x32x16_bf16 v[18:33], v[206:209], v[188:191], v[18:33]
	ds_read_b128 v[210:213], v101 offset:36864
	v_mfma_f32_32x32x16_bf16 v[2:17], v[206:209], v[192:195], v[2:17]
	ds_read_b128 v[222:225], v97 offset:36864
	s_waitcnt lgkmcnt(6)
	v_mfma_f32_32x32x16_bf16 v[50:65], v[236:239], v[240:243], v[50:65]
	s_waitcnt lgkmcnt(5)
	v_mfma_f32_32x32x16_bf16 v[34:49], v[236:239], v[244:247], v[34:49]
	s_waitcnt lgkmcnt(4)
	v_mfma_f32_32x32x16_bf16 v[18:33], v[248:251], v[240:243], v[18:33]
	v_mfma_f32_32x32x16_bf16 v[2:17], v[248:251], v[244:247], v[2:17]
	s_waitcnt lgkmcnt(2)
	v_mfma_f32_32x32x16_bf16 v[50:65], v[126:129], v[130:133], v[50:65]
	s_waitcnt lgkmcnt(1)
	v_mfma_f32_32x32x16_bf16 v[34:49], v[126:129], v[210:213], v[34:49]
	s_waitcnt lgkmcnt(0)
	v_mfma_f32_32x32x16_bf16 v[18:33], v[222:225], v[130:133], v[18:33]
	v_mfma_f32_32x32x16_bf16 v[2:17], v[222:225], v[210:213], v[2:17]
	s_nop 7
	s_nop 7
	s_barrier
	s_branch .LBB0_153

.LBB0_192:
	v_mov_b32_e32 v0, v1
	s_mul_hi_i32 s23, s22, 0x2e8ba2e9
	v_mbcnt_lo_u32_b32 v0, -1, v0
	v_mbcnt_hi_u32_b32 v0, -1, v0
	s_lshr_b32 s24, s23, 31
	s_ashr_i32 s23, s23, 3
	v_add_u32_e32 v90, s80, v0
	s_add_i32 s23, s23, s24
	s_mul_i32 s24, s23, 0xb00
	v_lshlrev_b32_e32 v0, 3, v90
	v_ashrrev_i32_e32 v89, 3, v90
	v_and_b32_e32 v88, 56, v0
	v_subrev_u32_e32 v0, s24, v89
	v_add_u32_e32 v0, s20, v0
	v_lshl_or_b32 v0, v0, 10, v88
	v_lshl_add_u64 v[72:73], v[0:1], 1, s[4:5]
	v_lshl_add_u32 v0, s23, 7, v89
	v_lshl_or_b32 v0, v0, 10, v88
	v_lshl_add_u64 v[74:75], v[0:1], 1, s[72:73]
	v_add_co_u32_e32 v76, vcc, s18, v74
	s_waitcnt lgkmcnt(0)
	s_nop 0
	v_addc_co_u32_e32 v77, vcc, 0, v75, vcc
	v_add_co_u32_e32 v78, vcc, s29, v74
	s_nop 0
	s_nop 0
	v_addc_co_u32_e32 v79, vcc, 0, v75, vcc
	v_add_co_u32_e32 v80, vcc, s10, v74
	s_nop 0
	s_nop 0
	v_addc_co_u32_e32 v81, vcc, 0, v75, vcc
	s_nop 0
	s_nop 0
	s_mov_b32 s24, 0x580000
	v_add_co_u32_e32 v82, vcc, s24, v72
	s_mov_b32 s24, 0x590000
	s_nop 0
	v_addc_co_u32_e32 v83, vcc, 0, v73, vcc
	v_add_co_u32_e32 v84, vcc, s18, v72
	s_nop 0
	s_nop 0
	v_addc_co_u32_e32 v85, vcc, 0, v73, vcc
	v_add_co_u32_e32 v86, vcc, s24, v72
	s_nop 0
	s_nop 0
	v_addc_co_u32_e32 v87, vcc, 0, v73, vcc
	s_nop 0
	v_mul_lo_u32 v34, v89, s27
	v_add_lshl_u32 v92, v34, v88, 1
	s_barrier
	v_and_b32_e32 v0, 31, v90
	v_add_u32_e32 v93, 0xd800, v92
	v_ashrrev_i32_e32 v2, 1, v90
	v_and_b32_e32 v91, 0xffffffc0, v2
	v_bfe_u32 v102, v90, 4, 3
	v_lshlrev_b32_e32 v102, 4, v102
	v_xor_b32_e32 v74, v102, v74
	v_xor_b32_e32 v76, v102, v76
	v_xor_b32_e32 v78, v102, v78
	v_xor_b32_e32 v80, v102, v80
	v_xor_b32_e32 v72, v102, v72
	v_xor_b32_e32 v82, v102, v82
	v_xor_b32_e32 v84, v102, v84
	v_xor_b32_e32 v86, v102, v86
	v_bfe_u32 v102, v90, 5, 1
	v_bfe_u32 v103, v90, 1, 3
	v_xor_b32_e32 v102, v102, v103
	v_lshlrev_b32_e32 v102, 4, v102
	v_lshrrev_b32_e32 v103, 1, v90
	v_and_b32_e32 v103, 64, v103
	v_and_b32_e32 v104, 31, v90
	v_or_b32_e32 v103, v103, v104
	v_lshl_or_b32 v94, v103, 7, v102
	v_and_b32_e32 v103, 0x5f, v90
	v_lshl_or_b32 v98, v103, 7, v102
	v_add_u32_e32 v98, 0x4000, v98
	v_xor_b32_e32 v95, 0x20, v94
	v_xor_b32_e32 v99, 0x20, v98
	v_xor_b32_e32 v96, 0x40, v94
	v_xor_b32_e32 v100, 0x40, v98
	v_xor_b32_e32 v97, 0x60, v94
	v_xor_b32_e32 v101, 0x60, v98
	v_mov_b32_e32 v214, 0x80
	v_mov_b32_e32 v215, 0
	s_lshl_b32 vcc_lo, s80, 4
	v_mov_b32_e32 v2, 0
	v_mov_b32_e32 v3, 0
	v_mov_b32_e32 v4, 0
	v_mov_b32_e32 v5, 0
	v_mov_b32_e32 v6, 0
	v_mov_b32_e32 v7, 0
	v_mov_b32_e32 v8, 0
	v_mov_b32_e32 v9, 0
	v_mov_b32_e32 v10, 0
	v_mov_b32_e32 v11, 0
	v_mov_b32_e32 v12, 0
	v_mov_b32_e32 v13, 0
	v_mov_b32_e32 v14, 0
	v_mov_b32_e32 v15, 0
	v_mov_b32_e32 v16, 0
	v_mov_b32_e32 v17, 0
	v_mov_b32_e32 v18, 0
	v_mov_b32_e32 v19, 0
	v_mov_b32_e32 v20, 0
	v_mov_b32_e32 v21, 0
	v_mov_b32_e32 v22, 0
	v_mov_b32_e32 v23, 0
	v_mov_b32_e32 v24, 0
	v_mov_b32_e32 v25, 0
	v_mov_b32_e32 v26, 0
	v_mov_b32_e32 v27, 0
	v_mov_b32_e32 v28, 0
	v_mov_b32_e32 v29, 0
	v_mov_b32_e32 v30, 0
	v_mov_b32_e32 v31, 0
	v_mov_b32_e32 v32, 0
	v_mov_b32_e32 v33, 0
	v_mov_b32_e32 v34, 0
	v_mov_b32_e32 v35, 0
	v_mov_b32_e32 v36, 0
	v_mov_b32_e32 v37, 0
	v_mov_b32_e32 v38, 0
	v_mov_b32_e32 v39, 0
	v_mov_b32_e32 v40, 0
	v_mov_b32_e32 v41, 0
	v_mov_b32_e32 v42, 0
	v_mov_b32_e32 v43, 0
	v_mov_b32_e32 v44, 0
	v_mov_b32_e32 v45, 0
	v_mov_b32_e32 v46, 0
	v_mov_b32_e32 v47, 0
	v_mov_b32_e32 v48, 0
	v_mov_b32_e32 v49, 0
	v_mov_b32_e32 v50, 0
	v_mov_b32_e32 v51, 0
	v_mov_b32_e32 v52, 0
	v_mov_b32_e32 v53, 0
	v_mov_b32_e32 v54, 0
	v_mov_b32_e32 v55, 0
	v_mov_b32_e32 v56, 0
	v_mov_b32_e32 v57, 0
	v_mov_b32_e32 v58, 0
	v_mov_b32_e32 v59, 0
	v_mov_b32_e32 v60, 0
	v_mov_b32_e32 v61, 0
	v_mov_b32_e32 v62, 0
	v_mov_b32_e32 v63, 0
	v_mov_b32_e32 v64, 0
	v_mov_b32_e32 v65, 0
	s_mov_b32 m0, vcc_lo
	s_nop 0
	global_load_lds_dwordx4 v[74:75], off
	s_add_u32 m0, vcc_lo, 0x1000
	s_nop 0
	global_load_lds_dwordx4 v[76:77], off
	s_add_u32 m0, vcc_lo, 0x2000
	s_nop 0
	global_load_lds_dwordx4 v[78:79], off
	s_add_u32 m0, vcc_lo, 0x3000
	s_nop 0
	global_load_lds_dwordx4 v[80:81], off
	s_add_u32 m0, vcc_lo, 0x4000
	s_nop 0
	global_load_lds_dwordx4 v[72:73], off
	s_add_u32 m0, vcc_lo, 0x5000
	s_nop 0
	global_load_lds_dwordx4 v[82:83], off
	s_add_u32 m0, vcc_lo, 0x6000
	s_nop 0
	global_load_lds_dwordx4 v[84:85], off
	s_add_u32 m0, vcc_lo, 0x7000
	s_nop 0
	global_load_lds_dwordx4 v[86:87], off
	v_lshl_add_u64 v[74:75], v[74:75], 0, v[214:215]
	v_lshl_add_u64 v[76:77], v[76:77], 0, v[214:215]
	v_lshl_add_u64 v[78:79], v[78:79], 0, v[214:215]
	v_lshl_add_u64 v[80:81], v[80:81], 0, v[214:215]
	v_lshl_add_u64 v[72:73], v[72:73], 0, v[214:215]
	v_lshl_add_u64 v[82:83], v[82:83], 0, v[214:215]
	v_lshl_add_u64 v[84:85], v[84:85], 0, v[214:215]
	v_lshl_add_u64 v[86:87], v[86:87], 0, v[214:215]
	s_add_u32 m0, vcc_lo, 0x8000
	s_nop 0
	global_load_lds_dwordx4 v[74:75], off
	s_add_u32 m0, vcc_lo, 0x9000
	s_nop 0
	global_load_lds_dwordx4 v[76:77], off
	s_add_u32 m0, vcc_lo, 0xa000
	s_nop 0
	global_load_lds_dwordx4 v[78:79], off
	s_add_u32 m0, vcc_lo, 0xb000
	s_nop 0
	global_load_lds_dwordx4 v[80:81], off
	s_add_u32 m0, vcc_lo, 0xc000
	s_nop 0
	global_load_lds_dwordx4 v[72:73], off
	s_add_u32 m0, vcc_lo, 0xd000
	s_nop 0
	global_load_lds_dwordx4 v[82:83], off
	s_add_u32 m0, vcc_lo, 0xe000
	s_nop 0
	global_load_lds_dwordx4 v[84:85], off
	s_add_u32 m0, vcc_lo, 0xf000
	s_nop 0
	global_load_lds_dwordx4 v[86:87], off
	v_lshl_add_u64 v[74:75], v[74:75], 0, v[214:215]
	v_lshl_add_u64 v[76:77], v[76:77], 0, v[214:215]
	v_lshl_add_u64 v[78:79], v[78:79], 0, v[214:215]
	v_lshl_add_u64 v[80:81], v[80:81], 0, v[214:215]
	v_lshl_add_u64 v[72:73], v[72:73], 0, v[214:215]
	v_lshl_add_u64 v[82:83], v[82:83], 0, v[214:215]
	v_lshl_add_u64 v[84:85], v[84:85], 0, v[214:215]
	v_lshl_add_u64 v[86:87], v[86:87], 0, v[214:215]
	s_mov_b32 vcc_hi, 7
	s_waitcnt vmcnt(8)
	s_barrier
	ds_read_b128 v[166:169], v94
	ds_read_b128 v[170:173], v98
	ds_read_b128 v[174:177], v98 offset:4096
	ds_read_b128 v[178:181], v94 offset:4096
	ds_read_b128 v[182:185], v95
	ds_read_b128 v[188:191], v99
	ds_read_b128 v[192:195], v99 offset:4096
	ds_read_b128 v[206:209], v95 offset:4096
	s_waitcnt lgkmcnt(6)
	v_mfma_f32_32x32x16_bf16 v[34:49], v[166:169], v[170:173], v[34:49]
	ds_read_b128 v[236:239], v96
	s_waitcnt lgkmcnt(6)
	v_mfma_f32_32x32x16_bf16 v[50:65], v[166:169], v[174:177], v[50:65]
	ds_read_b128 v[240:243], v100
	s_waitcnt lgkmcnt(6)
	v_mfma_f32_32x32x16_bf16 v[2:17], v[178:181], v[170:173], v[2:17]
	ds_read_b128 v[244:247], v100 offset:4096
	v_mfma_f32_32x32x16_bf16 v[18:33], v[178:181], v[174:177], v[18:33]
	ds_read_b128 v[248:251], v96 offset:4096
	s_waitcnt lgkmcnt(6)
	v_mfma_f32_32x32x16_bf16 v[34:49], v[182:185], v[188:191], v[34:49]
	ds_read_b128 v[126:129], v97
	s_waitcnt lgkmcnt(6)
	v_mfma_f32_32x32x16_bf16 v[50:65], v[182:185], v[192:195], v[50:65]
	ds_read_b128 v[130:133], v101
	s_waitcnt lgkmcnt(6)
	v_mfma_f32_32x32x16_bf16 v[2:17], v[206:209], v[188:191], v[2:17]
	ds_read_b128 v[210:213], v101 offset:4096
	v_mfma_f32_32x32x16_bf16 v[18:33], v[206:209], v[192:195], v[18:33]
	ds_read_b128 v[222:225], v97 offset:4096
	s_waitcnt vmcnt(0) lgkmcnt(0)
	s_barrier
.Lg_ffnin_loop:
	v_mfma_f32_32x32x16_bf16 v[34:49], v[236:239], v[240:243], v[34:49]
	s_mov_b32 m0, vcc_lo
	ds_read_b128 v[166:169], v94 offset:32768
	global_load_lds_dwordx4 v[74:75], off
	v_mfma_f32_32x32x16_bf16 v[50:65], v[236:239], v[244:247], v[50:65]
	s_add_u32 m0, vcc_lo, 0x1000
	ds_read_b128 v[170:173], v98 offset:32768
	global_load_lds_dwordx4 v[76:77], off
	v_mfma_f32_32x32x16_bf16 v[2:17], v[248:251], v[240:243], v[2:17]
	s_add_u32 m0, vcc_lo, 0x2000
	ds_read_b128 v[174:177], v98 offset:36864
	global_load_lds_dwordx4 v[78:79], off
	v_mfma_f32_32x32x16_bf16 v[18:33], v[248:251], v[244:247], v[18:33]
	s_add_u32 m0, vcc_lo, 0x3000
	ds_read_b128 v[178:181], v94 offset:36864
	global_load_lds_dwordx4 v[80:81], off
	v_mfma_f32_32x32x16_bf16 v[34:49], v[126:129], v[130:133], v[34:49]
	s_add_u32 m0, vcc_lo, 0x4000
	ds_read_b128 v[182:185], v95 offset:32768
	global_load_lds_dwordx4 v[72:73], off
	v_mfma_f32_32x32x16_bf16 v[50:65], v[126:129], v[210:213], v[50:65]
	s_add_u32 m0, vcc_lo, 0x5000
	ds_read_b128 v[188:191], v99 offset:32768
	global_load_lds_dwordx4 v[82:83], off
	v_mfma_f32_32x32x16_bf16 v[2:17], v[222:225], v[130:133], v[2:17]
	s_add_u32 m0, vcc_lo, 0x6000
	ds_read_b128 v[192:195], v99 offset:36864
	global_load_lds_dwordx4 v[84:85], off
	v_mfma_f32_32x32x16_bf16 v[18:33], v[222:225], v[210:213], v[18:33]
	s_add_u32 m0, vcc_lo, 0x7000
	ds_read_b128 v[206:209], v95 offset:36864
	global_load_lds_dwordx4 v[86:87], off
	s_waitcnt lgkmcnt(6)
	v_mfma_f32_32x32x16_bf16 v[34:49], v[166:169], v[170:173], v[34:49]
	ds_read_b128 v[236:239], v96 offset:32768
	v_lshl_add_u64 v[74:75], v[74:75], 0, v[214:215]
	v_lshl_add_u64 v[76:77], v[76:77], 0, v[214:215]
	v_lshl_add_u64 v[78:79], v[78:79], 0, v[214:215]
	v_lshl_add_u64 v[80:81], v[80:81], 0, v[214:215]
	v_lshl_add_u64 v[72:73], v[72:73], 0, v[214:215]
	v_lshl_add_u64 v[82:83], v[82:83], 0, v[214:215]
	v_lshl_add_u64 v[84:85], v[84:85], 0, v[214:215]
	v_lshl_add_u64 v[86:87], v[86:87], 0, v[214:215]
	s_waitcnt lgkmcnt(6)
	v_mfma_f32_32x32x16_bf16 v[50:65], v[166:169], v[174:177], v[50:65]
	ds_read_b128 v[240:243], v100 offset:32768
	s_waitcnt lgkmcnt(6)
	v_mfma_f32_32x32x16_bf16 v[2:17], v[178:181], v[170:173], v[2:17]
	ds_read_b128 v[244:247], v100 offset:36864
	v_mfma_f32_32x32x16_bf16 v[18:33], v[178:181], v[174:177], v[18:33]
	ds_read_b128 v[248:251], v96 offset:36864
	s_waitcnt lgkmcnt(6)
	v_mfma_f32_32x32x16_bf16 v[34:49], v[182:185], v[188:191], v[34:49]
	ds_read_b128 v[126:129], v97 offset:32768
	s_waitcnt lgkmcnt(6)
	v_mfma_f32_32x32x16_bf16 v[50:65], v[182:185], v[192:195], v[50:65]
	ds_read_b128 v[130:133], v101 offset:32768
	s_waitcnt lgkmcnt(6)
	v_mfma_f32_32x32x16_bf16 v[2:17], v[206:209], v[188:191], v[2:17]
	ds_read_b128 v[210:213], v101 offset:36864
	v_mfma_f32_32x32x16_bf16 v[18:33], v[206:209], v[192:195], v[18:33]
	ds_read_b128 v[222:225], v97 offset:36864
	s_waitcnt vmcnt(0) lgkmcnt(0)
	s_barrier
	v_mfma_f32_32x32x16_bf16 v[34:49], v[236:239], v[240:243], v[34:49]
	s_add_u32 m0, vcc_lo, 0x8000
	ds_read_b128 v[166:169], v94
	global_load_lds_dwordx4 v[74:75], off
	v_mfma_f32_32x32x16_bf16 v[50:65], v[236:239], v[244:247], v[50:65]
	s_add_u32 m0, vcc_lo, 0x9000
	ds_read_b128 v[170:173], v98
	global_load_lds_dwordx4 v[76:77], off
	v_mfma_f32_32x32x16_bf16 v[2:17], v[248:251], v[240:243], v[2:17]
	s_add_u32 m0, vcc_lo, 0xa000
	ds_read_b128 v[174:177], v98 offset:4096
	global_load_lds_dwordx4 v[78:79], off
	v_mfma_f32_32x32x16_bf16 v[18:33], v[248:251], v[244:247], v[18:33]
	s_add_u32 m0, vcc_lo, 0xb000
	ds_read_b128 v[178:181], v94 offset:4096
	global_load_lds_dwordx4 v[80:81], off
	v_mfma_f32_32x32x16_bf16 v[34:49], v[126:129], v[130:133], v[34:49]
	s_add_u32 m0, vcc_lo, 0xc000
	ds_read_b128 v[182:185], v95
	global_load_lds_dwordx4 v[72:73], off
	v_mfma_f32_32x32x16_bf16 v[50:65], v[126:129], v[210:213], v[50:65]
	s_add_u32 m0, vcc_lo, 0xd000
	ds_read_b128 v[188:191], v99
	global_load_lds_dwordx4 v[82:83], off
	v_mfma_f32_32x32x16_bf16 v[2:17], v[222:225], v[130:133], v[2:17]
	s_add_u32 m0, vcc_lo, 0xe000
	ds_read_b128 v[192:195], v99 offset:4096
	global_load_lds_dwordx4 v[84:85], off
	v_mfma_f32_32x32x16_bf16 v[18:33], v[222:225], v[210:213], v[18:33]
	s_add_u32 m0, vcc_lo, 0xf000
	ds_read_b128 v[206:209], v95 offset:4096
	global_load_lds_dwordx4 v[86:87], off
	s_waitcnt lgkmcnt(6)
	v_mfma_f32_32x32x16_bf16 v[34:49], v[166:169], v[170:173], v[34:49]
	ds_read_b128 v[236:239], v96
	v_lshl_add_u64 v[74:75], v[74:75], 0, v[214:215]
	v_lshl_add_u64 v[76:77], v[76:77], 0, v[214:215]
	v_lshl_add_u64 v[78:79], v[78:79], 0, v[214:215]
	v_lshl_add_u64 v[80:81], v[80:81], 0, v[214:215]
	v_lshl_add_u64 v[72:73], v[72:73], 0, v[214:215]
	v_lshl_add_u64 v[82:83], v[82:83], 0, v[214:215]
	v_lshl_add_u64 v[84:85], v[84:85], 0, v[214:215]
	v_lshl_add_u64 v[86:87], v[86:87], 0, v[214:215]
	s_waitcnt lgkmcnt(6)
	v_mfma_f32_32x32x16_bf16 v[50:65], v[166:169], v[174:177], v[50:65]
	ds_read_b128 v[240:243], v100
	s_waitcnt lgkmcnt(6)
	v_mfma_f32_32x32x16_bf16 v[2:17], v[178:181], v[170:173], v[2:17]
	ds_read_b128 v[244:247], v100 offset:4096
	v_mfma_f32_32x32x16_bf16 v[18:33], v[178:181], v[174:177], v[18:33]
	ds_read_b128 v[248:251], v96 offset:4096
	s_waitcnt lgkmcnt(6)
	v_mfma_f32_32x32x16_bf16 v[34:49], v[182:185], v[188:191], v[34:49]
	ds_read_b128 v[126:129], v97
	s_waitcnt lgkmcnt(6)
	v_mfma_f32_32x32x16_bf16 v[50:65], v[182:185], v[192:195], v[50:65]
	ds_read_b128 v[130:133], v101
	s_waitcnt lgkmcnt(6)
	v_mfma_f32_32x32x16_bf16 v[2:17], v[206:209], v[188:191], v[2:17]
	ds_read_b128 v[210:213], v101 offset:4096
	v_mfma_f32_32x32x16_bf16 v[18:33], v[206:209], v[192:195], v[18:33]
	ds_read_b128 v[222:225], v97 offset:4096
	s_waitcnt vmcnt(0) lgkmcnt(0)
	s_barrier
	s_sub_u32 vcc_hi, vcc_hi, 1
	s_cmp_lg_u32 vcc_hi, 0
	s_cbranch_scc1 .Lg_ffnin_loop
	v_mfma_f32_32x32x16_bf16 v[34:49], v[236:239], v[240:243], v[34:49]
	ds_read_b128 v[166:169], v94 offset:32768
	v_mfma_f32_32x32x16_bf16 v[50:65], v[236:239], v[244:247], v[50:65]
	ds_read_b128 v[170:173], v98 offset:32768
	v_mfma_f32_32x32x16_bf16 v[2:17], v[248:251], v[240:243], v[2:17]
	ds_read_b128 v[174:177], v98 offset:36864
	v_mfma_f32_32x32x16_bf16 v[18:33], v[248:251], v[244:247], v[18:33]
	ds_read_b128 v[178:181], v94 offset:36864
	v_mfma_f32_32x32x16_bf16 v[34:49], v[126:129], v[130:133], v[34:49]
	ds_read_b128 v[182:185], v95 offset:32768
	v_mfma_f32_32x32x16_bf16 v[50:65], v[126:129], v[210:213], v[50:65]
	ds_read_b128 v[188:191], v99 offset:32768
	v_mfma_f32_32x32x16_bf16 v[2:17], v[222:225], v[130:133], v[2:17]
	ds_read_b128 v[192:195], v99 offset:36864
	v_mfma_f32_32x32x16_bf16 v[18:33], v[222:225], v[210:213], v[18:33]
	ds_read_b128 v[206:209], v95 offset:36864
	s_waitcnt lgkmcnt(6)
	v_mfma_f32_32x32x16_bf16 v[34:49], v[166:169], v[170:173], v[34:49]
	ds_read_b128 v[236:239], v96 offset:32768
	s_waitcnt lgkmcnt(6)
	v_mfma_f32_32x32x16_bf16 v[50:65], v[166:169], v[174:177], v[50:65]
	ds_read_b128 v[240:243], v100 offset:32768
	s_waitcnt lgkmcnt(6)
	v_mfma_f32_32x32x16_bf16 v[2:17], v[178:181], v[170:173], v[2:17]
	ds_read_b128 v[244:247], v100 offset:36864
	v_mfma_f32_32x32x16_bf16 v[18:33], v[178:181], v[174:177], v[18:33]
	ds_read_b128 v[248:251], v96 offset:36864
	s_waitcnt lgkmcnt(6)
	v_mfma_f32_32x32x16_bf16 v[34:49], v[182:185], v[188:191], v[34:49]
	ds_read_b128 v[126:129], v97 offset:32768
	s_waitcnt lgkmcnt(6)
	v_mfma_f32_32x32x16_bf16 v[50:65], v[182:185], v[192:195], v[50:65]
	ds_read_b128 v[130:133], v101 offset:32768
	s_waitcnt lgkmcnt(6)
	v_mfma_f32_32x32x16_bf16 v[2:17], v[206:209], v[188:191], v[2:17]
	ds_read_b128 v[210:213], v101 offset:36864
	v_mfma_f32_32x32x16_bf16 v[18:33], v[206:209], v[192:195], v[18:33]
	ds_read_b128 v[222:225], v97 offset:36864
	s_waitcnt lgkmcnt(6)
	v_mfma_f32_32x32x16_bf16 v[34:49], v[236:239], v[240:243], v[34:49]
	s_waitcnt lgkmcnt(5)
	v_mfma_f32_32x32x16_bf16 v[50:65], v[236:239], v[244:247], v[50:65]
	s_waitcnt lgkmcnt(4)
	v_mfma_f32_32x32x16_bf16 v[2:17], v[248:251], v[240:243], v[2:17]
	v_mfma_f32_32x32x16_bf16 v[18:33], v[248:251], v[244:247], v[18:33]
	s_waitcnt lgkmcnt(2)
	v_mfma_f32_32x32x16_bf16 v[34:49], v[126:129], v[130:133], v[34:49]
	s_waitcnt lgkmcnt(1)
	v_mfma_f32_32x32x16_bf16 v[50:65], v[126:129], v[210:213], v[50:65]
	s_waitcnt lgkmcnt(0)
	v_mfma_f32_32x32x16_bf16 v[2:17], v[222:225], v[130:133], v[2:17]
	v_mfma_f32_32x32x16_bf16 v[18:33], v[222:225], v[210:213], v[18:33]
	s_nop 7
	s_nop 7
	v_mul_f32_e32 v67, 0xbfb8aa3b, v34
	v_exp_f32_e32 v67, v67
	v_lshrrev_b32_e32 v66, 3, v90
	v_lshlrev_b32_e32 v0, 1, v0
	v_and_or_b32 v66, v66, 4, v91
	v_add_f32_e32 v67, 1.0, v67
	v_rcp_f32_e32 v67, v67
	v_and_or_b32 v0, v90, 64, v0
	s_barrier
	v_mul_f32_e32 v34, v34, v67
	v_mad_u64_u32 v[66:67], s[24:25], v66, s28, v[0:1]
	v_mul_f32_e32 v0, 0xbfb8aa3b, v35
	v_exp_f32_e32 v0, v0
	v_mul_f32_e32 v34, v50, v34
	v_cvt_pk_bf16_f32 v34, v34, s0
	v_add_f32_e32 v0, 1.0, v0
	v_rcp_f32_e32 v0, v0
	ds_write_b16 v66, v34
	s_mul_i32 s23, s23, 0x57500
	s_add_i32 s22, s22, s81
	v_mul_f32_e32 v0, v35, v0
	v_mul_f32_e32 v0, v51, v0
	v_cvt_pk_bf16_f32 v0, v0, s0
	ds_write_b16 v66, v0 offset:144
	v_mul_f32_e32 v0, 0xbfb8aa3b, v36
	v_exp_f32_e32 v0, v0
	s_nop 0
	v_add_f32_e32 v0, 1.0, v0
	v_rcp_f32_e32 v0, v0
	s_nop 0
	v_mul_f32_e32 v0, v36, v0
	v_mul_f32_e32 v0, v52, v0
	v_cvt_pk_bf16_f32 v0, v0, s0
	ds_write_b16 v66, v0 offset:288
	v_mul_f32_e32 v0, 0xbfb8aa3b, v37
	v_exp_f32_e32 v0, v0
	s_nop 0
	v_add_f32_e32 v0, 1.0, v0
	v_rcp_f32_e32 v0, v0
	s_nop 0
	v_mul_f32_e32 v0, v37, v0
	v_mul_f32_e32 v0, v53, v0
	v_cvt_pk_bf16_f32 v0, v0, s0
	ds_write_b16 v66, v0 offset:432
	v_mul_f32_e32 v0, 0xbfb8aa3b, v38
	v_exp_f32_e32 v0, v0
	s_nop 0
	v_add_f32_e32 v0, 1.0, v0
	v_rcp_f32_e32 v0, v0
	s_nop 0
	v_mul_f32_e32 v0, v38, v0
	v_mul_f32_e32 v0, v54, v0
	v_cvt_pk_bf16_f32 v0, v0, s0
	ds_write_b16 v66, v0 offset:1152
	v_mul_f32_e32 v0, 0xbfb8aa3b, v39
	v_exp_f32_e32 v0, v0
	s_nop 0
	v_add_f32_e32 v0, 1.0, v0
	v_rcp_f32_e32 v0, v0
	s_nop 0
	v_mul_f32_e32 v0, v39, v0
	v_mul_f32_e32 v0, v55, v0
	v_cvt_pk_bf16_f32 v0, v0, s0
	ds_write_b16 v66, v0 offset:1296
	v_mul_f32_e32 v0, 0xbfb8aa3b, v40
	v_exp_f32_e32 v0, v0
	s_nop 0
	v_add_f32_e32 v0, 1.0, v0
	v_rcp_f32_e32 v0, v0
	s_nop 0
	v_mul_f32_e32 v0, v40, v0
	v_mul_f32_e32 v0, v56, v0
	v_cvt_pk_bf16_f32 v0, v0, s0
	ds_write_b16 v66, v0 offset:1440
	v_mul_f32_e32 v0, 0xbfb8aa3b, v41
	v_exp_f32_e32 v0, v0
	s_nop 0
	v_add_f32_e32 v0, 1.0, v0
	v_rcp_f32_e32 v0, v0
	s_nop 0
	v_mul_f32_e32 v0, v41, v0
	v_mul_f32_e32 v0, v57, v0
	v_cvt_pk_bf16_f32 v0, v0, s0
	ds_write_b16 v66, v0 offset:1584
	v_mul_f32_e32 v0, 0xbfb8aa3b, v42
	v_exp_f32_e32 v0, v0
	s_nop 0
	v_add_f32_e32 v0, 1.0, v0
	v_rcp_f32_e32 v0, v0
	s_nop 0
	v_mul_f32_e32 v0, v42, v0
	v_mul_f32_e32 v0, v58, v0
	v_cvt_pk_bf16_f32 v0, v0, s0
	ds_write_b16 v66, v0 offset:2304
	v_mul_f32_e32 v0, 0xbfb8aa3b, v43
	v_exp_f32_e32 v0, v0
	s_nop 0
	v_add_f32_e32 v0, 1.0, v0
	v_rcp_f32_e32 v0, v0
	s_nop 0
	v_mul_f32_e32 v0, v43, v0
	v_mul_f32_e32 v0, v59, v0
	v_cvt_pk_bf16_f32 v0, v0, s0
	ds_write_b16 v66, v0 offset:2448
	v_mul_f32_e32 v0, 0xbfb8aa3b, v44
	v_exp_f32_e32 v0, v0
	s_nop 0
	v_add_f32_e32 v0, 1.0, v0
	v_rcp_f32_e32 v0, v0
	s_nop 0
	v_mul_f32_e32 v0, v44, v0
	v_mul_f32_e32 v0, v60, v0
	v_cvt_pk_bf16_f32 v0, v0, s0
	ds_write_b16 v66, v0 offset:2592
	v_mul_f32_e32 v0, 0xbfb8aa3b, v45
	v_exp_f32_e32 v0, v0
	s_nop 0
	v_add_f32_e32 v0, 1.0, v0
	v_rcp_f32_e32 v0, v0
	s_nop 0
	v_mul_f32_e32 v0, v45, v0
	v_mul_f32_e32 v0, v61, v0
	v_cvt_pk_bf16_f32 v0, v0, s0
	ds_write_b16 v66, v0 offset:2736
	v_mul_f32_e32 v0, 0xbfb8aa3b, v46
	v_exp_f32_e32 v0, v0
	s_nop 0
	v_add_f32_e32 v0, 1.0, v0
	v_rcp_f32_e32 v0, v0
	s_nop 0
	v_mul_f32_e32 v0, v46, v0
	v_mul_f32_e32 v0, v62, v0
	v_cvt_pk_bf16_f32 v0, v0, s0
	ds_write_b16 v66, v0 offset:3456
	v_mul_f32_e32 v0, 0xbfb8aa3b, v47
	v_exp_f32_e32 v0, v0
	s_nop 0
	v_add_f32_e32 v0, 1.0, v0
	v_rcp_f32_e32 v0, v0
	s_nop 0
	v_mul_f32_e32 v0, v47, v0
	v_mul_f32_e32 v0, v63, v0
	v_cvt_pk_bf16_f32 v0, v0, s0
	ds_write_b16 v66, v0 offset:3600
	v_mul_f32_e32 v0, 0xbfb8aa3b, v48
	v_exp_f32_e32 v0, v0
	s_nop 0
	v_add_f32_e32 v0, 1.0, v0
	v_rcp_f32_e32 v0, v0
	s_nop 0
	v_mul_f32_e32 v0, v48, v0
	v_mul_f32_e32 v0, v64, v0
	v_cvt_pk_bf16_f32 v0, v0, s0
	ds_write_b16 v66, v0 offset:3744
	v_mul_f32_e32 v0, 0xbfb8aa3b, v49
	v_exp_f32_e32 v0, v0
	s_nop 0
	v_add_f32_e32 v0, 1.0, v0
	v_rcp_f32_e32 v0, v0
	s_nop 0
	v_mul_f32_e32 v0, v49, v0
	v_mul_f32_e32 v0, v65, v0
	v_cvt_pk_bf16_f32 v0, v0, s0
	ds_write_b16 v66, v0 offset:3888
	v_mul_f32_e32 v0, 0xbfb8aa3b, v2
	v_exp_f32_e32 v0, v0
	s_nop 0
	v_add_f32_e32 v0, 1.0, v0
	v_rcp_f32_e32 v0, v0
	s_nop 0
	v_mul_f32_e32 v0, v2, v0
	v_mul_f32_e32 v0, v18, v0
	v_cvt_pk_bf16_f32 v0, v0, s0
	ds_write_b16 v66, v0 offset:4608
	v_mul_f32_e32 v0, 0xbfb8aa3b, v3
	v_exp_f32_e32 v0, v0
	s_nop 0
	v_add_f32_e32 v0, 1.0, v0
	v_rcp_f32_e32 v0, v0
	s_nop 0
	v_mul_f32_e32 v0, v3, v0
	v_mul_f32_e32 v0, v19, v0
	v_cvt_pk_bf16_f32 v0, v0, s0
	ds_write_b16 v66, v0 offset:4752
	v_mul_f32_e32 v0, 0xbfb8aa3b, v4
	v_exp_f32_e32 v0, v0
	s_nop 0
	v_add_f32_e32 v0, 1.0, v0
	v_rcp_f32_e32 v0, v0
	s_nop 0
	v_mul_f32_e32 v0, v4, v0
	v_mul_f32_e32 v0, v20, v0
	v_cvt_pk_bf16_f32 v0, v0, s0
	ds_write_b16 v66, v0 offset:4896
	v_mul_f32_e32 v0, 0xbfb8aa3b, v5
	v_exp_f32_e32 v0, v0
	s_nop 0
	v_add_f32_e32 v0, 1.0, v0
	v_rcp_f32_e32 v0, v0
	s_nop 0
	v_mul_f32_e32 v0, v5, v0
	v_mul_f32_e32 v0, v21, v0
	v_cvt_pk_bf16_f32 v0, v0, s0
	ds_write_b16 v66, v0 offset:5040
	v_mul_f32_e32 v0, 0xbfb8aa3b, v6
	v_exp_f32_e32 v0, v0
	s_nop 0
	v_add_f32_e32 v0, 1.0, v0
	v_rcp_f32_e32 v0, v0
	s_nop 0
	v_mul_f32_e32 v0, v6, v0
	v_mul_f32_e32 v0, v22, v0
	v_cvt_pk_bf16_f32 v0, v0, s0
	ds_write_b16 v66, v0 offset:5760
	v_mul_f32_e32 v0, 0xbfb8aa3b, v7
	v_exp_f32_e32 v0, v0
	s_nop 0
	v_add_f32_e32 v0, 1.0, v0
	v_rcp_f32_e32 v0, v0
	s_nop 0
	v_mul_f32_e32 v0, v7, v0
	v_mul_f32_e32 v0, v23, v0
	v_cvt_pk_bf16_f32 v0, v0, s0
	ds_write_b16 v66, v0 offset:5904
	v_mul_f32_e32 v0, 0xbfb8aa3b, v8
	v_exp_f32_e32 v0, v0
	s_nop 0
	v_add_f32_e32 v0, 1.0, v0
	v_rcp_f32_e32 v0, v0
	s_nop 0
	v_mul_f32_e32 v0, v8, v0
	v_mul_f32_e32 v0, v24, v0
	v_cvt_pk_bf16_f32 v0, v0, s0
	ds_write_b16 v66, v0 offset:6048
	v_mul_f32_e32 v0, 0xbfb8aa3b, v9
	v_exp_f32_e32 v0, v0
	s_nop 0
	v_add_f32_e32 v0, 1.0, v0
	v_rcp_f32_e32 v0, v0
	s_nop 0
	v_mul_f32_e32 v0, v9, v0
	v_mul_f32_e32 v0, v25, v0
	v_cvt_pk_bf16_f32 v0, v0, s0
	ds_write_b16 v66, v0 offset:6192
	v_mul_f32_e32 v0, 0xbfb8aa3b, v10
	v_exp_f32_e32 v0, v0
	s_nop 0
	v_add_f32_e32 v0, 1.0, v0
	v_rcp_f32_e32 v0, v0
	s_nop 0
	v_mul_f32_e32 v0, v10, v0
	v_mul_f32_e32 v0, v26, v0
	v_cvt_pk_bf16_f32 v0, v0, s0
	ds_write_b16 v66, v0 offset:6912
	v_mul_f32_e32 v0, 0xbfb8aa3b, v11
	v_exp_f32_e32 v0, v0
	s_nop 0
	v_add_f32_e32 v0, 1.0, v0
	v_rcp_f32_e32 v0, v0
	s_nop 0
	v_mul_f32_e32 v0, v11, v0
	v_mul_f32_e32 v0, v27, v0
	v_cvt_pk_bf16_f32 v0, v0, s0
	ds_write_b16 v66, v0 offset:7056
	v_mul_f32_e32 v0, 0xbfb8aa3b, v12
	v_exp_f32_e32 v0, v0
	s_nop 0
	v_add_f32_e32 v0, 1.0, v0
	v_rcp_f32_e32 v0, v0
	s_nop 0
	v_mul_f32_e32 v0, v12, v0
	v_mul_f32_e32 v0, v28, v0
	v_cvt_pk_bf16_f32 v0, v0, s0
	ds_write_b16 v66, v0 offset:7200
	v_mul_f32_e32 v0, 0xbfb8aa3b, v13
	v_exp_f32_e32 v0, v0
	s_nop 0
	v_add_f32_e32 v0, 1.0, v0
	v_rcp_f32_e32 v0, v0
	s_nop 0
	v_mul_f32_e32 v0, v13, v0
	v_mul_f32_e32 v0, v29, v0
	v_cvt_pk_bf16_f32 v0, v0, s0
	ds_write_b16 v66, v0 offset:7344
	v_mul_f32_e32 v0, 0xbfb8aa3b, v14
	v_exp_f32_e32 v0, v0
	s_nop 0
	v_add_f32_e32 v0, 1.0, v0
	v_rcp_f32_e32 v0, v0
	s_nop 0
	v_mul_f32_e32 v0, v14, v0
	v_mul_f32_e32 v0, v30, v0
	v_cvt_pk_bf16_f32 v0, v0, s0
	ds_write_b16 v66, v0 offset:8064
	v_mul_f32_e32 v0, 0xbfb8aa3b, v15
	v_exp_f32_e32 v0, v0
	s_nop 0
	v_add_f32_e32 v0, 1.0, v0
	v_rcp_f32_e32 v0, v0
	s_nop 0
	v_mul_f32_e32 v0, v15, v0
	v_mul_f32_e32 v0, v31, v0
	v_cvt_pk_bf16_f32 v0, v0, s0
	ds_write_b16 v66, v0 offset:8208
	v_mul_f32_e32 v0, 0xbfb8aa3b, v16
	v_exp_f32_e32 v0, v0
	s_nop 0
	v_add_f32_e32 v0, 1.0, v0
	v_rcp_f32_e32 v0, v0
	s_nop 0
	v_mul_f32_e32 v0, v16, v0
	v_mul_f32_e32 v0, v32, v0
	v_cvt_pk_bf16_f32 v0, v0, s0
	ds_write_b16 v66, v0 offset:8352
	v_mul_f32_e32 v0, 0xbfb8aa3b, v17
	v_exp_f32_e32 v0, v0
	s_nop 0
	v_add_f32_e32 v0, 1.0, v0
	v_rcp_f32_e32 v0, v0
	s_nop 0
	v_mul_f32_e32 v0, v17, v0
	v_mul_f32_e32 v0, v33, v0
	v_cvt_pk_bf16_f32 v0, v0, s0
	ds_write_b16 v66, v0 offset:8496
	v_mul_lo_u32 v0, v89, s28
	v_lshl_add_u32 v8, v88, 1, v0
	s_waitcnt lgkmcnt(0)
	s_barrier
	ds_read_b128 v[2:5], v8
	v_mul_lo_u32 v0, v89, s26
	v_add_u32_e32 v0, s23, v0
	v_or_b32_e32 v0, v0, v88
	v_add_u32_e32 v0, s20, v0
	v_lshl_add_u64 v[6:7], v[0:1], 1, s[90:91]
	s_waitcnt lgkmcnt(0)
	global_store_dwordx4 v[6:7], v[2:5], off
	ds_read_b128 v[2:5], v8 offset:4608
	v_add_u32_e32 v6, 0x16000, v0
	v_mov_b32_e32 v7, v1
	v_lshl_add_u64 v[6:7], v[6:7], 1, s[90:91]
	s_add_i32 s20, s20, s21
	s_waitcnt lgkmcnt(0)
	global_store_dwordx4 v[6:7], v[2:5], off
	ds_read_b128 v[2:5], v8 offset:9216
	v_add_u32_e32 v6, 0x2c000, v0
	v_mov_b32_e32 v7, v1
	v_lshl_add_u64 v[6:7], v[6:7], 1, s[90:91]
	v_add_u32_e32 v0, 0x42000, v0
	s_waitcnt lgkmcnt(0)
	global_store_dwordx4 v[6:7], v[2:5], off
	ds_read_b128 v[2:5], v8 offset:13824
	v_lshl_add_u64 v[6:7], v[0:1], 1, s[90:91]
	s_cmpk_gt_i32 s22, 0xaff
	s_waitcnt lgkmcnt(0)
	global_store_dwordx4 v[6:7], v[2:5], off
	s_cbranch_scc0 .LBB0_192
	s_movk_i32 s96, 0x48
	s_mov_b32 s19, 0x80000
	s_mov_b32 s14, 0xdb629599
	s_mov_b32 s15, 0xf534ddc0
	s_mov_b32 s16, 0xfc2757d1
	s_mov_b64 s[12:13], s[30:31]
	v_readlane_b32 s22, v255, 2
	v_readlane_b32 s23, v255, 3

.LBB0_206:
	v_mov_b32_e32 v0, v1
	s_and_b32 s34, s25, 0x380
	v_mbcnt_lo_u32_b32 v0, -1, v0
	v_mbcnt_hi_u32_b32 v0, -1, v0
	v_add_u32_e32 v88, s80, v0
	s_and_b32 s31, s24, 0xffffff80
	v_lshlrev_b32_e32 v0, 3, v88
	s_waitcnt lgkmcnt(0)
	v_ashrrev_i32_e32 v2, 3, v88
	v_and_b32_e32 v34, 56, v0
	v_add_u32_e32 v0, s34, v2
	v_lshl_or_b32 v0, v0, 10, v34
	v_lshl_add_u64 v[72:73], v[0:1], 1, s[4:5]
	v_add_u32_e32 v0, s31, v2
	v_lshl_or_b32 v0, v0, 10, v34
	v_lshl_add_u64 v[74:75], v[0:1], 1, s[72:73]
	v_add_co_u32_e32 v76, vcc, s18, v74
	s_mov_b32 s20, 0x20000
	s_nop 0
	v_addc_co_u32_e32 v77, vcc, 0, v75, vcc
	v_add_co_u32_e32 v78, vcc, s20, v74
	v_mul_lo_u32 v35, v2, s96
	s_nop 0
	v_addc_co_u32_e32 v79, vcc, 0, v75, vcc
	v_add_co_u32_e32 v80, vcc, s10, v74
	s_nop 0
	s_nop 0
	v_addc_co_u32_e32 v81, vcc, 0, v75, vcc
	s_nop 0
	s_nop 0
	s_nop 0
	v_add_co_u32_e32 v82, vcc, s18, v72
	v_add_lshl_u32 v90, v35, v34, 1
	s_nop 0
	v_addc_co_u32_e32 v83, vcc, 0, v73, vcc
	v_add_co_u32_e32 v84, vcc, s20, v72
	s_nop 0
	s_nop 0
	v_addc_co_u32_e32 v85, vcc, 0, v73, vcc
	v_add_co_u32_e32 v86, vcc, s10, v72
	s_nop 0
	s_nop 0
	v_addc_co_u32_e32 v87, vcc, 0, v73, vcc
	s_nop 0
	s_barrier
	v_and_b32_e32 v0, 31, v88
	s_movk_i32 s20, 0x90
	v_add_u32_e32 v91, 0xd800, v90
	v_ashrrev_i32_e32 v2, 1, v88
	v_and_b32_e32 v89, 0xffffffc0, v2
	v_bfe_u32 v102, v88, 4, 3
	v_lshlrev_b32_e32 v102, 4, v102
	v_xor_b32_e32 v74, v102, v74
	v_xor_b32_e32 v76, v102, v76
	v_xor_b32_e32 v78, v102, v78
	v_xor_b32_e32 v80, v102, v80
	v_xor_b32_e32 v72, v102, v72
	v_xor_b32_e32 v82, v102, v82
	v_xor_b32_e32 v84, v102, v84
	v_xor_b32_e32 v86, v102, v86
	v_bfe_u32 v102, v88, 5, 1
	v_bfe_u32 v103, v88, 1, 3
	v_xor_b32_e32 v102, v102, v103
	v_lshlrev_b32_e32 v102, 4, v102
	v_lshrrev_b32_e32 v103, 1, v88
	v_and_b32_e32 v103, 64, v103
	v_and_b32_e32 v104, 31, v88
	v_or_b32_e32 v103, v103, v104
	v_lshl_or_b32 v94, v103, 7, v102
	v_and_b32_e32 v103, 0x5f, v88
	v_lshl_or_b32 v98, v103, 7, v102
	v_add_u32_e32 v98, 0x4000, v98
	v_xor_b32_e32 v95, 0x20, v94
	v_xor_b32_e32 v99, 0x20, v98
	v_xor_b32_e32 v96, 0x40, v94
	v_xor_b32_e32 v100, 0x40, v98
	v_xor_b32_e32 v97, 0x60, v94
	v_xor_b32_e32 v101, 0x60, v98
	v_mov_b32_e32 v214, 0x80
	v_mov_b32_e32 v215, 0
	s_lshl_b32 vcc_lo, s80, 4
	v_mov_b32_e32 v2, 0
	v_mov_b32_e32 v3, 0
	v_mov_b32_e32 v4, 0
	v_mov_b32_e32 v5, 0
	v_mov_b32_e32 v6, 0
	v_mov_b32_e32 v7, 0
	v_mov_b32_e32 v8, 0
	v_mov_b32_e32 v9, 0
	v_mov_b32_e32 v10, 0
	v_mov_b32_e32 v11, 0
	v_mov_b32_e32 v12, 0
	v_mov_b32_e32 v13, 0
	v_mov_b32_e32 v14, 0
	v_mov_b32_e32 v15, 0
	v_mov_b32_e32 v16, 0
	v_mov_b32_e32 v17, 0
	v_mov_b32_e32 v18, 0
	v_mov_b32_e32 v19, 0
	v_mov_b32_e32 v20, 0
	v_mov_b32_e32 v21, 0
	v_mov_b32_e32 v22, 0
	v_mov_b32_e32 v23, 0
	v_mov_b32_e32 v24, 0
	v_mov_b32_e32 v25, 0
	v_mov_b32_e32 v26, 0
	v_mov_b32_e32 v27, 0
	v_mov_b32_e32 v28, 0
	v_mov_b32_e32 v29, 0
	v_mov_b32_e32 v30, 0
	v_mov_b32_e32 v31, 0
	v_mov_b32_e32 v32, 0
	v_mov_b32_e32 v33, 0
	v_mov_b32_e32 v34, 0
	v_mov_b32_e32 v35, 0
	v_mov_b32_e32 v36, 0
	v_mov_b32_e32 v37, 0
	v_mov_b32_e32 v38, 0
	v_mov_b32_e32 v39, 0
	v_mov_b32_e32 v40, 0
	v_mov_b32_e32 v41, 0
	v_mov_b32_e32 v42, 0
	v_mov_b32_e32 v43, 0
	v_mov_b32_e32 v44, 0
	v_mov_b32_e32 v45, 0
	v_mov_b32_e32 v46, 0
	v_mov_b32_e32 v47, 0
	v_mov_b32_e32 v48, 0
	v_mov_b32_e32 v49, 0
	v_mov_b32_e32 v50, 0
	v_mov_b32_e32 v51, 0
	v_mov_b32_e32 v52, 0
	v_mov_b32_e32 v53, 0
	v_mov_b32_e32 v54, 0
	v_mov_b32_e32 v55, 0
	v_mov_b32_e32 v56, 0
	v_mov_b32_e32 v57, 0
	v_mov_b32_e32 v58, 0
	v_mov_b32_e32 v59, 0
	v_mov_b32_e32 v60, 0
	v_mov_b32_e32 v61, 0
	v_mov_b32_e32 v62, 0
	v_mov_b32_e32 v63, 0
	v_mov_b32_e32 v64, 0
	v_mov_b32_e32 v65, 0
	s_mov_b32 m0, vcc_lo
	s_nop 0
	global_load_lds_dwordx4 v[74:75], off
	s_add_u32 m0, vcc_lo, 0x1000
	s_nop 0
	global_load_lds_dwordx4 v[76:77], off
	s_add_u32 m0, vcc_lo, 0x2000
	s_nop 0
	global_load_lds_dwordx4 v[78:79], off
	s_add_u32 m0, vcc_lo, 0x3000
	s_nop 0
	global_load_lds_dwordx4 v[80:81], off
	s_add_u32 m0, vcc_lo, 0x4000
	s_nop 0
	global_load_lds_dwordx4 v[72:73], off
	s_add_u32 m0, vcc_lo, 0x5000
	s_nop 0
	global_load_lds_dwordx4 v[82:83], off
	s_add_u32 m0, vcc_lo, 0x6000
	s_nop 0
	global_load_lds_dwordx4 v[84:85], off
	s_add_u32 m0, vcc_lo, 0x7000
	s_nop 0
	global_load_lds_dwordx4 v[86:87], off
	v_lshl_add_u64 v[74:75], v[74:75], 0, v[214:215]
	v_lshl_add_u64 v[76:77], v[76:77], 0, v[214:215]
	v_lshl_add_u64 v[78:79], v[78:79], 0, v[214:215]
	v_lshl_add_u64 v[80:81], v[80:81], 0, v[214:215]
	v_lshl_add_u64 v[72:73], v[72:73], 0, v[214:215]
	v_lshl_add_u64 v[82:83], v[82:83], 0, v[214:215]
	v_lshl_add_u64 v[84:85], v[84:85], 0, v[214:215]
	v_lshl_add_u64 v[86:87], v[86:87], 0, v[214:215]
	s_add_u32 m0, vcc_lo, 0x8000
	s_nop 0
	global_load_lds_dwordx4 v[74:75], off
	s_add_u32 m0, vcc_lo, 0x9000
	s_nop 0
	global_load_lds_dwordx4 v[76:77], off
	s_add_u32 m0, vcc_lo, 0xa000
	s_nop 0
	global_load_lds_dwordx4 v[78:79], off
	s_add_u32 m0, vcc_lo, 0xb000
	s_nop 0
	global_load_lds_dwordx4 v[80:81], off
	s_add_u32 m0, vcc_lo, 0xc000
	s_nop 0
	global_load_lds_dwordx4 v[72:73], off
	s_add_u32 m0, vcc_lo, 0xd000
	s_nop 0
	global_load_lds_dwordx4 v[82:83], off
	s_add_u32 m0, vcc_lo, 0xe000
	s_nop 0
	global_load_lds_dwordx4 v[84:85], off
	s_add_u32 m0, vcc_lo, 0xf000
	s_nop 0
	global_load_lds_dwordx4 v[86:87], off
	v_lshl_add_u64 v[74:75], v[74:75], 0, v[214:215]
	v_lshl_add_u64 v[76:77], v[76:77], 0, v[214:215]
	v_lshl_add_u64 v[78:79], v[78:79], 0, v[214:215]
	v_lshl_add_u64 v[80:81], v[80:81], 0, v[214:215]
	v_lshl_add_u64 v[72:73], v[72:73], 0, v[214:215]
	v_lshl_add_u64 v[82:83], v[82:83], 0, v[214:215]
	v_lshl_add_u64 v[84:85], v[84:85], 0, v[214:215]
	v_lshl_add_u64 v[86:87], v[86:87], 0, v[214:215]
	s_mov_b32 vcc_hi, 7
	s_waitcnt vmcnt(8)
	s_barrier
	ds_read_b128 v[166:169], v94
	ds_read_b128 v[170:173], v98
	ds_read_b128 v[174:177], v98 offset:4096
	ds_read_b128 v[178:181], v94 offset:4096
	ds_read_b128 v[182:185], v95
	ds_read_b128 v[188:191], v99
	ds_read_b128 v[192:195], v99 offset:4096
	ds_read_b128 v[206:209], v95 offset:4096
	s_waitcnt lgkmcnt(6)
	v_mfma_f32_32x32x16_bf16 v[34:49], v[166:169], v[170:173], v[34:49]
	ds_read_b128 v[236:239], v96
	s_waitcnt lgkmcnt(6)
	v_mfma_f32_32x32x16_bf16 v[50:65], v[166:169], v[174:177], v[50:65]
	ds_read_b128 v[240:243], v100
	s_waitcnt lgkmcnt(6)
	v_mfma_f32_32x32x16_bf16 v[2:17], v[178:181], v[170:173], v[2:17]
	ds_read_b128 v[244:247], v100 offset:4096
	v_mfma_f32_32x32x16_bf16 v[18:33], v[178:181], v[174:177], v[18:33]
	ds_read_b128 v[248:251], v96 offset:4096
	s_waitcnt lgkmcnt(6)
	v_mfma_f32_32x32x16_bf16 v[34:49], v[182:185], v[188:191], v[34:49]
	ds_read_b128 v[126:129], v97
	s_waitcnt lgkmcnt(6)
	v_mfma_f32_32x32x16_bf16 v[50:65], v[182:185], v[192:195], v[50:65]
	ds_read_b128 v[130:133], v101
	s_waitcnt lgkmcnt(6)
	v_mfma_f32_32x32x16_bf16 v[2:17], v[206:209], v[188:191], v[2:17]
	ds_read_b128 v[210:213], v101 offset:4096
	v_mfma_f32_32x32x16_bf16 v[18:33], v[206:209], v[192:195], v[18:33]
	ds_read_b128 v[222:225], v97 offset:4096
	s_waitcnt vmcnt(0) lgkmcnt(0)
	s_barrier
.Lg_resid0_loop:
	v_mfma_f32_32x32x16_bf16 v[34:49], v[236:239], v[240:243], v[34:49]
	s_mov_b32 m0, vcc_lo
	ds_read_b128 v[166:169], v94 offset:32768
	global_load_lds_dwordx4 v[74:75], off
	v_mfma_f32_32x32x16_bf16 v[50:65], v[236:239], v[244:247], v[50:65]
	s_add_u32 m0, vcc_lo, 0x1000
	ds_read_b128 v[170:173], v98 offset:32768
	global_load_lds_dwordx4 v[76:77], off
	v_mfma_f32_32x32x16_bf16 v[2:17], v[248:251], v[240:243], v[2:17]
	s_add_u32 m0, vcc_lo, 0x2000
	ds_read_b128 v[174:177], v98 offset:36864
	global_load_lds_dwordx4 v[78:79], off
	v_mfma_f32_32x32x16_bf16 v[18:33], v[248:251], v[244:247], v[18:33]
	s_add_u32 m0, vcc_lo, 0x3000
	ds_read_b128 v[178:181], v94 offset:36864
	global_load_lds_dwordx4 v[80:81], off
	v_mfma_f32_32x32x16_bf16 v[34:49], v[126:129], v[130:133], v[34:49]
	s_add_u32 m0, vcc_lo, 0x4000
	ds_read_b128 v[182:185], v95 offset:32768
	global_load_lds_dwordx4 v[72:73], off
	v_mfma_f32_32x32x16_bf16 v[50:65], v[126:129], v[210:213], v[50:65]
	s_add_u32 m0, vcc_lo, 0x5000
	ds_read_b128 v[188:191], v99 offset:32768
	global_load_lds_dwordx4 v[82:83], off
	v_mfma_f32_32x32x16_bf16 v[2:17], v[222:225], v[130:133], v[2:17]
	s_add_u32 m0, vcc_lo, 0x6000
	ds_read_b128 v[192:195], v99 offset:36864
	global_load_lds_dwordx4 v[84:85], off
	v_mfma_f32_32x32x16_bf16 v[18:33], v[222:225], v[210:213], v[18:33]
	s_add_u32 m0, vcc_lo, 0x7000
	ds_read_b128 v[206:209], v95 offset:36864
	global_load_lds_dwordx4 v[86:87], off
	s_waitcnt lgkmcnt(6)
	v_mfma_f32_32x32x16_bf16 v[34:49], v[166:169], v[170:173], v[34:49]
	ds_read_b128 v[236:239], v96 offset:32768
	v_lshl_add_u64 v[74:75], v[74:75], 0, v[214:215]
	v_lshl_add_u64 v[76:77], v[76:77], 0, v[214:215]
	v_lshl_add_u64 v[78:79], v[78:79], 0, v[214:215]
	v_lshl_add_u64 v[80:81], v[80:81], 0, v[214:215]
	v_lshl_add_u64 v[72:73], v[72:73], 0, v[214:215]
	v_lshl_add_u64 v[82:83], v[82:83], 0, v[214:215]
	v_lshl_add_u64 v[84:85], v[84:85], 0, v[214:215]
	v_lshl_add_u64 v[86:87], v[86:87], 0, v[214:215]
	s_waitcnt lgkmcnt(6)
	v_mfma_f32_32x32x16_bf16 v[50:65], v[166:169], v[174:177], v[50:65]
	ds_read_b128 v[240:243], v100 offset:32768
	s_waitcnt lgkmcnt(6)
	v_mfma_f32_32x32x16_bf16 v[2:17], v[178:181], v[170:173], v[2:17]
	ds_read_b128 v[244:247], v100 offset:36864
	v_mfma_f32_32x32x16_bf16 v[18:33], v[178:181], v[174:177], v[18:33]
	ds_read_b128 v[248:251], v96 offset:36864
	s_waitcnt lgkmcnt(6)
	v_mfma_f32_32x32x16_bf16 v[34:49], v[182:185], v[188:191], v[34:49]
	ds_read_b128 v[126:129], v97 offset:32768
	s_waitcnt lgkmcnt(6)
	v_mfma_f32_32x32x16_bf16 v[50:65], v[182:185], v[192:195], v[50:65]
	ds_read_b128 v[130:133], v101 offset:32768
	s_waitcnt lgkmcnt(6)
	v_mfma_f32_32x32x16_bf16 v[2:17], v[206:209], v[188:191], v[2:17]
	ds_read_b128 v[210:213], v101 offset:36864
	v_mfma_f32_32x32x16_bf16 v[18:33], v[206:209], v[192:195], v[18:33]
	ds_read_b128 v[222:225], v97 offset:36864
	s_waitcnt vmcnt(0) lgkmcnt(0)
	s_barrier
	v_mfma_f32_32x32x16_bf16 v[34:49], v[236:239], v[240:243], v[34:49]
	s_add_u32 m0, vcc_lo, 0x8000
	ds_read_b128 v[166:169], v94
	global_load_lds_dwordx4 v[74:75], off
	v_mfma_f32_32x32x16_bf16 v[50:65], v[236:239], v[244:247], v[50:65]
	s_add_u32 m0, vcc_lo, 0x9000
	ds_read_b128 v[170:173], v98
	global_load_lds_dwordx4 v[76:77], off
	v_mfma_f32_32x32x16_bf16 v[2:17], v[248:251], v[240:243], v[2:17]
	s_add_u32 m0, vcc_lo, 0xa000
	ds_read_b128 v[174:177], v98 offset:4096
	global_load_lds_dwordx4 v[78:79], off
	v_mfma_f32_32x32x16_bf16 v[18:33], v[248:251], v[244:247], v[18:33]
	s_add_u32 m0, vcc_lo, 0xb000
	ds_read_b128 v[178:181], v94 offset:4096
	global_load_lds_dwordx4 v[80:81], off
	v_mfma_f32_32x32x16_bf16 v[34:49], v[126:129], v[130:133], v[34:49]
	s_add_u32 m0, vcc_lo, 0xc000
	ds_read_b128 v[182:185], v95
	global_load_lds_dwordx4 v[72:73], off
	v_mfma_f32_32x32x16_bf16 v[50:65], v[126:129], v[210:213], v[50:65]
	s_add_u32 m0, vcc_lo, 0xd000
	ds_read_b128 v[188:191], v99
	global_load_lds_dwordx4 v[82:83], off
	v_mfma_f32_32x32x16_bf16 v[2:17], v[222:225], v[130:133], v[2:17]
	s_add_u32 m0, vcc_lo, 0xe000
	ds_read_b128 v[192:195], v99 offset:4096
	global_load_lds_dwordx4 v[84:85], off
	v_mfma_f32_32x32x16_bf16 v[18:33], v[222:225], v[210:213], v[18:33]
	s_add_u32 m0, vcc_lo, 0xf000
	ds_read_b128 v[206:209], v95 offset:4096
	global_load_lds_dwordx4 v[86:87], off
	s_waitcnt lgkmcnt(6)
	v_mfma_f32_32x32x16_bf16 v[34:49], v[166:169], v[170:173], v[34:49]
	ds_read_b128 v[236:239], v96
	v_lshl_add_u64 v[74:75], v[74:75], 0, v[214:215]
	v_lshl_add_u64 v[76:77], v[76:77], 0, v[214:215]
	v_lshl_add_u64 v[78:79], v[78:79], 0, v[214:215]
	v_lshl_add_u64 v[80:81], v[80:81], 0, v[214:215]
	v_lshl_add_u64 v[72:73], v[72:73], 0, v[214:215]
	v_lshl_add_u64 v[82:83], v[82:83], 0, v[214:215]
	v_lshl_add_u64 v[84:85], v[84:85], 0, v[214:215]
	v_lshl_add_u64 v[86:87], v[86:87], 0, v[214:215]
	s_waitcnt lgkmcnt(6)
	v_mfma_f32_32x32x16_bf16 v[50:65], v[166:169], v[174:177], v[50:65]
	ds_read_b128 v[240:243], v100
	s_waitcnt lgkmcnt(6)
	v_mfma_f32_32x32x16_bf16 v[2:17], v[178:181], v[170:173], v[2:17]
	ds_read_b128 v[244:247], v100 offset:4096
	v_mfma_f32_32x32x16_bf16 v[18:33], v[178:181], v[174:177], v[18:33]
	ds_read_b128 v[248:251], v96 offset:4096
	s_waitcnt lgkmcnt(6)
	v_mfma_f32_32x32x16_bf16 v[34:49], v[182:185], v[188:191], v[34:49]
	ds_read_b128 v[126:129], v97
	s_waitcnt lgkmcnt(6)
	v_mfma_f32_32x32x16_bf16 v[50:65], v[182:185], v[192:195], v[50:65]
	ds_read_b128 v[130:133], v101
	s_waitcnt lgkmcnt(6)
	v_mfma_f32_32x32x16_bf16 v[2:17], v[206:209], v[188:191], v[2:17]
	ds_read_b128 v[210:213], v101 offset:4096
	v_mfma_f32_32x32x16_bf16 v[18:33], v[206:209], v[192:195], v[18:33]
	ds_read_b128 v[222:225], v97 offset:4096
	s_waitcnt vmcnt(0) lgkmcnt(0)
	s_barrier
	s_sub_u32 vcc_hi, vcc_hi, 1
	s_cmp_lg_u32 vcc_hi, 0
	s_cbranch_scc1 .Lg_resid0_loop
	v_mfma_f32_32x32x16_bf16 v[34:49], v[236:239], v[240:243], v[34:49]
	ds_read_b128 v[166:169], v94 offset:32768
	v_mfma_f32_32x32x16_bf16 v[50:65], v[236:239], v[244:247], v[50:65]
	ds_read_b128 v[170:173], v98 offset:32768
	v_mfma_f32_32x32x16_bf16 v[2:17], v[248:251], v[240:243], v[2:17]
	ds_read_b128 v[174:177], v98 offset:36864
	v_mfma_f32_32x32x16_bf16 v[18:33], v[248:251], v[244:247], v[18:33]
	ds_read_b128 v[178:181], v94 offset:36864
	v_mfma_f32_32x32x16_bf16 v[34:49], v[126:129], v[130:133], v[34:49]
	ds_read_b128 v[182:185], v95 offset:32768
	v_mfma_f32_32x32x16_bf16 v[50:65], v[126:129], v[210:213], v[50:65]
	ds_read_b128 v[188:191], v99 offset:32768
	v_mfma_f32_32x32x16_bf16 v[2:17], v[222:225], v[130:133], v[2:17]
	ds_read_b128 v[192:195], v99 offset:36864
	v_mfma_f32_32x32x16_bf16 v[18:33], v[222:225], v[210:213], v[18:33]
	ds_read_b128 v[206:209], v95 offset:36864
	s_waitcnt lgkmcnt(6)
	v_mfma_f32_32x32x16_bf16 v[34:49], v[166:169], v[170:173], v[34:49]
	ds_read_b128 v[236:239], v96 offset:32768
	s_waitcnt lgkmcnt(6)
	v_mfma_f32_32x32x16_bf16 v[50:65], v[166:169], v[174:177], v[50:65]
	ds_read_b128 v[240:243], v100 offset:32768
	s_waitcnt lgkmcnt(6)
	v_mfma_f32_32x32x16_bf16 v[2:17], v[178:181], v[170:173], v[2:17]
	ds_read_b128 v[244:247], v100 offset:36864
	v_mfma_f32_32x32x16_bf16 v[18:33], v[178:181], v[174:177], v[18:33]
	ds_read_b128 v[248:251], v96 offset:36864
	s_waitcnt lgkmcnt(6)
	v_mfma_f32_32x32x16_bf16 v[34:49], v[182:185], v[188:191], v[34:49]
	ds_read_b128 v[126:129], v97 offset:32768
	s_waitcnt lgkmcnt(6)
	v_mfma_f32_32x32x16_bf16 v[50:65], v[182:185], v[192:195], v[50:65]
	ds_read_b128 v[130:133], v101 offset:32768
	s_waitcnt lgkmcnt(6)
	v_mfma_f32_32x32x16_bf16 v[2:17], v[206:209], v[188:191], v[2:17]
	ds_read_b128 v[210:213], v101 offset:36864
	v_mfma_f32_32x32x16_bf16 v[18:33], v[206:209], v[192:195], v[18:33]
	ds_read_b128 v[222:225], v97 offset:36864
	s_waitcnt lgkmcnt(6)
	v_mfma_f32_32x32x16_bf16 v[34:49], v[236:239], v[240:243], v[34:49]
	s_waitcnt lgkmcnt(5)
	v_mfma_f32_32x32x16_bf16 v[50:65], v[236:239], v[244:247], v[50:65]
	s_waitcnt lgkmcnt(4)
	v_mfma_f32_32x32x16_bf16 v[2:17], v[248:251], v[240:243], v[2:17]
	v_mfma_f32_32x32x16_bf16 v[18:33], v[248:251], v[244:247], v[18:33]
	s_waitcnt lgkmcnt(2)
	v_mfma_f32_32x32x16_bf16 v[34:49], v[126:129], v[130:133], v[34:49]
	s_waitcnt lgkmcnt(1)
	v_mfma_f32_32x32x16_bf16 v[50:65], v[126:129], v[210:213], v[50:65]
	s_waitcnt lgkmcnt(0)
	v_mfma_f32_32x32x16_bf16 v[2:17], v[222:225], v[130:133], v[2:17]
	v_mfma_f32_32x32x16_bf16 v[18:33], v[222:225], v[210:213], v[18:33]
	s_nop 7
	s_nop 7
	s_andn2_b64 vcc, exec, s[22:23]
	s_mov_b64 s[20:21], s[26:27]
	s_barrier
	s_cbranch_vccnz .LBB0_205
	s_load_dwordx2 s[20:21], s[28:29], 0x0
	s_branch .LBB0_205
